# proj_resid epilogue: 8 residual-row loads in flight per thread, gate vector loaded once, counted vmcnt
# speedup vs baseline: 1.0102x; 1.0102x over previous
.LBB0_751:
	global_load_dwordx4 v[116:119], v[70:71], off
	v_lshl_add_u64 v[120:121], v[74:75], 0, s[10:11]
	v_lshl_add_u64 v[122:123], v[72:73], 0, s[10:11]
	s_mov_b32 s98, 0x8000
	s_mov_b32 s99, 0
	global_load_dwordx4 v[76:79], v[120:121], off
	v_lshl_add_u64 v[120:121], v[120:121], 0, s[98:99]
	global_load_dwordx4 v[80:83], v[120:121], off
	v_lshl_add_u64 v[120:121], v[120:121], 0, s[98:99]
	global_load_dwordx4 v[84:87], v[120:121], off
	v_lshl_add_u64 v[120:121], v[120:121], 0, s[98:99]
	global_load_dwordx4 v[88:91], v[120:121], off
	v_lshl_add_u64 v[120:121], v[120:121], 0, s[98:99]
	global_load_dwordx4 v[92:95], v[120:121], off
	v_lshl_add_u64 v[120:121], v[120:121], 0, s[98:99]
	global_load_dwordx4 v[96:99], v[120:121], off
	v_lshl_add_u64 v[120:121], v[120:121], 0, s[98:99]
	global_load_dwordx4 v[100:103], v[120:121], off
	v_lshl_add_u64 v[120:121], v[120:121], 0, s[98:99]
	global_load_dwordx4 v[104:107], v[120:121], off
	v_lshl_add_u64 v[120:121], v[120:121], 0, s[98:99]
	ds_read_b128 v[108:111], v65 offset:0
	ds_read_b128 v[112:115], v65 offset:4224
	s_waitcnt vmcnt(7) lgkmcnt(1)
	v_pk_fma_f32 v[76:77], v[108:109], v[116:117], v[76:77]
	v_pk_fma_f32 v[78:79], v[110:111], v[118:119], v[78:79]
	global_store_dwordx4 v[122:123], v[76:79], off
	v_lshl_add_u64 v[122:123], v[122:123], 0, s[98:99]
	ds_read_b128 v[108:111], v65 offset:8448
	s_waitcnt vmcnt(7) lgkmcnt(1)
	v_pk_fma_f32 v[80:81], v[112:113], v[116:117], v[80:81]
	v_pk_fma_f32 v[82:83], v[114:115], v[118:119], v[82:83]
	global_store_dwordx4 v[122:123], v[80:83], off
	v_lshl_add_u64 v[122:123], v[122:123], 0, s[98:99]
	ds_read_b128 v[112:115], v65 offset:12672
	s_waitcnt vmcnt(7) lgkmcnt(1)
	v_pk_fma_f32 v[84:85], v[108:109], v[116:117], v[84:85]
	v_pk_fma_f32 v[86:87], v[110:111], v[118:119], v[86:87]
	global_store_dwordx4 v[122:123], v[84:87], off
	v_lshl_add_u64 v[122:123], v[122:123], 0, s[98:99]
	ds_read_b128 v[108:111], v65 offset:16896
	s_waitcnt vmcnt(7) lgkmcnt(1)
	v_pk_fma_f32 v[88:89], v[112:113], v[116:117], v[88:89]
	v_pk_fma_f32 v[90:91], v[114:115], v[118:119], v[90:91]
	global_store_dwordx4 v[122:123], v[88:91], off
	v_lshl_add_u64 v[122:123], v[122:123], 0, s[98:99]
	ds_read_b128 v[112:115], v65 offset:21120
	s_waitcnt vmcnt(7) lgkmcnt(1)
	v_pk_fma_f32 v[92:93], v[108:109], v[116:117], v[92:93]
	v_pk_fma_f32 v[94:95], v[110:111], v[118:119], v[94:95]
	global_store_dwordx4 v[122:123], v[92:95], off
	v_lshl_add_u64 v[122:123], v[122:123], 0, s[98:99]
	ds_read_b128 v[108:111], v65 offset:25344
	s_waitcnt vmcnt(7) lgkmcnt(1)
	v_pk_fma_f32 v[96:97], v[112:113], v[116:117], v[96:97]
	v_pk_fma_f32 v[98:99], v[114:115], v[118:119], v[98:99]
	global_store_dwordx4 v[122:123], v[96:99], off
	v_lshl_add_u64 v[122:123], v[122:123], 0, s[98:99]
	ds_read_b128 v[112:115], v65 offset:29568
	s_waitcnt vmcnt(7) lgkmcnt(1)
	v_pk_fma_f32 v[100:101], v[108:109], v[116:117], v[100:101]
	v_pk_fma_f32 v[102:103], v[110:111], v[118:119], v[102:103]
	global_store_dwordx4 v[122:123], v[100:103], off
	v_lshl_add_u64 v[122:123], v[122:123], 0, s[98:99]
	s_waitcnt vmcnt(7) lgkmcnt(0)
	v_pk_fma_f32 v[104:105], v[112:113], v[116:117], v[104:105]
	v_pk_fma_f32 v[106:107], v[114:115], v[118:119], v[106:107]
	global_store_dwordx4 v[122:123], v[104:107], off
	v_lshl_add_u64 v[122:123], v[122:123], 0, s[98:99]
	global_load_dwordx4 v[76:79], v[120:121], off
	v_lshl_add_u64 v[120:121], v[120:121], 0, s[98:99]
	global_load_dwordx4 v[80:83], v[120:121], off
	v_lshl_add_u64 v[120:121], v[120:121], 0, s[98:99]
	global_load_dwordx4 v[84:87], v[120:121], off
	v_lshl_add_u64 v[120:121], v[120:121], 0, s[98:99]
	global_load_dwordx4 v[88:91], v[120:121], off
	v_lshl_add_u64 v[120:121], v[120:121], 0, s[98:99]
	global_load_dwordx4 v[92:95], v[120:121], off
	v_lshl_add_u64 v[120:121], v[120:121], 0, s[98:99]
	global_load_dwordx4 v[96:99], v[120:121], off
	v_lshl_add_u64 v[120:121], v[120:121], 0, s[98:99]
	global_load_dwordx4 v[100:103], v[120:121], off
	v_lshl_add_u64 v[120:121], v[120:121], 0, s[98:99]
	global_load_dwordx4 v[104:107], v[120:121], off
	v_lshl_add_u64 v[120:121], v[120:121], 0, s[98:99]
	ds_read_b128 v[108:111], v65 offset:33792
	ds_read_b128 v[112:115], v65 offset:38016
	s_waitcnt vmcnt(7) lgkmcnt(1)
	v_pk_fma_f32 v[76:77], v[108:109], v[116:117], v[76:77]
	v_pk_fma_f32 v[78:79], v[110:111], v[118:119], v[78:79]
	global_store_dwordx4 v[122:123], v[76:79], off
	v_lshl_add_u64 v[122:123], v[122:123], 0, s[98:99]
	ds_read_b128 v[108:111], v65 offset:42240
	s_waitcnt vmcnt(7) lgkmcnt(1)
	v_pk_fma_f32 v[80:81], v[112:113], v[116:117], v[80:81]
	v_pk_fma_f32 v[82:83], v[114:115], v[118:119], v[82:83]
	global_store_dwordx4 v[122:123], v[80:83], off
	v_lshl_add_u64 v[122:123], v[122:123], 0, s[98:99]
	ds_read_b128 v[112:115], v65 offset:46464
	s_waitcnt vmcnt(7) lgkmcnt(1)
	v_pk_fma_f32 v[84:85], v[108:109], v[116:117], v[84:85]
	v_pk_fma_f32 v[86:87], v[110:111], v[118:119], v[86:87]
	global_store_dwordx4 v[122:123], v[84:87], off
	v_lshl_add_u64 v[122:123], v[122:123], 0, s[98:99]
	ds_read_b128 v[108:111], v65 offset:50688
	s_waitcnt vmcnt(7) lgkmcnt(1)
	v_pk_fma_f32 v[88:89], v[112:113], v[116:117], v[88:89]
	v_pk_fma_f32 v[90:91], v[114:115], v[118:119], v[90:91]
	global_store_dwordx4 v[122:123], v[88:91], off
	v_lshl_add_u64 v[122:123], v[122:123], 0, s[98:99]
	ds_read_b128 v[112:115], v65 offset:54912
	s_waitcnt vmcnt(7) lgkmcnt(1)
	v_pk_fma_f32 v[92:93], v[108:109], v[116:117], v[92:93]
	v_pk_fma_f32 v[94:95], v[110:111], v[118:119], v[94:95]
	global_store_dwordx4 v[122:123], v[92:95], off
	v_lshl_add_u64 v[122:123], v[122:123], 0, s[98:99]
	ds_read_b128 v[108:111], v65 offset:59136
	s_waitcnt vmcnt(7) lgkmcnt(1)
	v_pk_fma_f32 v[96:97], v[112:113], v[116:117], v[96:97]
	v_pk_fma_f32 v[98:99], v[114:115], v[118:119], v[98:99]
	global_store_dwordx4 v[122:123], v[96:99], off
	v_lshl_add_u64 v[122:123], v[122:123], 0, s[98:99]
	ds_read_b128 v[112:115], v65 offset:63360
	s_waitcnt vmcnt(7) lgkmcnt(1)
	v_pk_fma_f32 v[100:101], v[108:109], v[116:117], v[100:101]
	v_pk_fma_f32 v[102:103], v[110:111], v[118:119], v[102:103]
	global_store_dwordx4 v[122:123], v[100:103], off
	v_lshl_add_u64 v[122:123], v[122:123], 0, s[98:99]
	s_waitcnt vmcnt(7) lgkmcnt(0)
	v_pk_fma_f32 v[104:105], v[112:113], v[116:117], v[104:105]
	v_pk_fma_f32 v[106:107], v[114:115], v[118:119], v[106:107]
	global_store_dwordx4 v[122:123], v[104:107], off
	v_lshl_add_u64 v[122:123], v[122:123], 0, s[98:99]
	v_add_u32_e32 v65, 0x10800, v65
	s_mov_b32 s10, 0x80000
	s_mov_b32 s11, 0
	s_barrier
	ds_write_b128 v141, v[60:63]
	ds_write_b128 v141, v[48:51] offset:64
	ds_write_b128 v141, v[44:47] offset:8448
	ds_write_b128 v141, v[40:43] offset:8512
	ds_write_b128 v141, v[36:39] offset:16896
	ds_write_b128 v141, v[32:35] offset:16960
	ds_write_b128 v141, v[28:31] offset:25344
	ds_write_b128 v141, v[24:27] offset:25408
	ds_write_b128 v141, v[20:23] offset:33792
	ds_write_b128 v141, v[16:19] offset:33856
	ds_write_b128 v141, v[12:15] offset:42240
	ds_write_b128 v141, v[8:11] offset:42304
	ds_write_b128 v141, v[4:7] offset:50688
	ds_write_b128 v141, v[0:3] offset:50752
	ds_write_b128 v141, v[52:55] offset:59136
	ds_write_b128 v141, v[56:59] offset:59200
	s_waitcnt lgkmcnt(0)
	s_barrier
	s_and_saveexec_b64 s[10:11], s[4:5]
	s_xor_b64 s[4:5], exec, s[10:11]
	v_add_u32_e32 v136, 0xffffc000, v64
	v_lshlrev_b64 v[0:1], 12, v[136:137]
	v_lshl_add_u64 v[4:5], s[56:57], 0, v[0:1]
	v_lshl_add_u64 v[2:3], s[70:71], 0, v[0:1]
	s_or_saveexec_b64 s[4:5], s[4:5]
	v_mov_b64_e32 v[0:1], 0xc000
	s_xor_b64 exec, exec, s[4:5]
	v_ashrrev_i32_e32 v65, 31, v64
	v_lshlrev_b64 v[0:1], 12, v[64:65]
	v_lshl_add_u64 v[4:5], s[52:53], 0, v[0:1]
	v_lshl_add_u64 v[2:3], s[84:85], 0, v[0:1]
	v_ashrrev_i32_e32 v0, 11, v64
	v_mul_hi_i32_i24_e32 v1, 0x1800, v0
	v_mul_i32_i24_e32 v0, 0x1800, v0
	s_or_b64 exec, exec, s[4:5]
	v_lshl_add_u64 v[0:1], v[0:1], 2, s[0:1]
	v_lshl_add_u64 v[0:1], s[8:9], 2, v[0:1]
	v_lshlrev_b32_e32 v136, 2, v66
	v_lshl_add_u64 v[0:1], v[0:1], 0, v[136:137]
	v_lshl_add_u64 v[2:3], v[2:3], 0, v[68:69]
	v_lshl_add_u64 v[4:5], v[4:5], 0, v[68:69]
	s_mov_b64 s[4:5], 0
.LBB0_757:
	global_load_dwordx4 v[48:51], v[0:1], off offset:512
	v_lshl_add_u64 v[52:53], v[4:5], 0, s[4:5]
	v_lshl_add_u64 v[54:55], v[2:3], 0, s[4:5]
	s_mov_b32 s98, 0x8000
	s_mov_b32 s99, 0
	global_load_dwordx4 v[8:11], v[52:53], off offset:512
	v_lshl_add_u64 v[52:53], v[52:53], 0, s[98:99]
	global_load_dwordx4 v[12:15], v[52:53], off offset:512
	v_lshl_add_u64 v[52:53], v[52:53], 0, s[98:99]
	global_load_dwordx4 v[16:19], v[52:53], off offset:512
	v_lshl_add_u64 v[52:53], v[52:53], 0, s[98:99]
	global_load_dwordx4 v[20:23], v[52:53], off offset:512
	v_lshl_add_u64 v[52:53], v[52:53], 0, s[98:99]
	global_load_dwordx4 v[24:27], v[52:53], off offset:512
	v_lshl_add_u64 v[52:53], v[52:53], 0, s[98:99]
	global_load_dwordx4 v[28:31], v[52:53], off offset:512
	v_lshl_add_u64 v[52:53], v[52:53], 0, s[98:99]
	global_load_dwordx4 v[32:35], v[52:53], off offset:512
	v_lshl_add_u64 v[52:53], v[52:53], 0, s[98:99]
	global_load_dwordx4 v[36:39], v[52:53], off offset:512
	v_lshl_add_u64 v[52:53], v[52:53], 0, s[98:99]
	ds_read_b128 v[40:43], v67 offset:0
	ds_read_b128 v[44:47], v67 offset:4224
	s_waitcnt vmcnt(7) lgkmcnt(1)
	v_pk_fma_f32 v[8:9], v[40:41], v[48:49], v[8:9]
	v_pk_fma_f32 v[10:11], v[42:43], v[50:51], v[10:11]
	global_store_dwordx4 v[54:55], v[8:11], off offset:512
	v_lshl_add_u64 v[54:55], v[54:55], 0, s[98:99]
	ds_read_b128 v[40:43], v67 offset:8448
	s_waitcnt vmcnt(7) lgkmcnt(1)
	v_pk_fma_f32 v[12:13], v[44:45], v[48:49], v[12:13]
	v_pk_fma_f32 v[14:15], v[46:47], v[50:51], v[14:15]
	global_store_dwordx4 v[54:55], v[12:15], off offset:512
	v_lshl_add_u64 v[54:55], v[54:55], 0, s[98:99]
	ds_read_b128 v[44:47], v67 offset:12672
	s_waitcnt vmcnt(7) lgkmcnt(1)
	v_pk_fma_f32 v[16:17], v[40:41], v[48:49], v[16:17]
	v_pk_fma_f32 v[18:19], v[42:43], v[50:51], v[18:19]
	global_store_dwordx4 v[54:55], v[16:19], off offset:512
	v_lshl_add_u64 v[54:55], v[54:55], 0, s[98:99]
	ds_read_b128 v[40:43], v67 offset:16896
	s_waitcnt vmcnt(7) lgkmcnt(1)
	v_pk_fma_f32 v[20:21], v[44:45], v[48:49], v[20:21]
	v_pk_fma_f32 v[22:23], v[46:47], v[50:51], v[22:23]
	global_store_dwordx4 v[54:55], v[20:23], off offset:512
	v_lshl_add_u64 v[54:55], v[54:55], 0, s[98:99]
	ds_read_b128 v[44:47], v67 offset:21120
	s_waitcnt vmcnt(7) lgkmcnt(1)
	v_pk_fma_f32 v[24:25], v[40:41], v[48:49], v[24:25]
	v_pk_fma_f32 v[26:27], v[42:43], v[50:51], v[26:27]
	global_store_dwordx4 v[54:55], v[24:27], off offset:512
	v_lshl_add_u64 v[54:55], v[54:55], 0, s[98:99]
	ds_read_b128 v[40:43], v67 offset:25344
	s_waitcnt vmcnt(7) lgkmcnt(1)
	v_pk_fma_f32 v[28:29], v[44:45], v[48:49], v[28:29]
	v_pk_fma_f32 v[30:31], v[46:47], v[50:51], v[30:31]
	global_store_dwordx4 v[54:55], v[28:31], off offset:512
	v_lshl_add_u64 v[54:55], v[54:55], 0, s[98:99]
	ds_read_b128 v[44:47], v67 offset:29568
	s_waitcnt vmcnt(7) lgkmcnt(1)
	v_pk_fma_f32 v[32:33], v[40:41], v[48:49], v[32:33]
	v_pk_fma_f32 v[34:35], v[42:43], v[50:51], v[34:35]
	global_store_dwordx4 v[54:55], v[32:35], off offset:512
	v_lshl_add_u64 v[54:55], v[54:55], 0, s[98:99]
	s_waitcnt vmcnt(7) lgkmcnt(0)
	v_pk_fma_f32 v[36:37], v[44:45], v[48:49], v[36:37]
	v_pk_fma_f32 v[38:39], v[46:47], v[50:51], v[38:39]
	global_store_dwordx4 v[54:55], v[36:39], off offset:512
	v_lshl_add_u64 v[54:55], v[54:55], 0, s[98:99]
	global_load_dwordx4 v[8:11], v[52:53], off offset:512
	v_lshl_add_u64 v[52:53], v[52:53], 0, s[98:99]
	global_load_dwordx4 v[12:15], v[52:53], off offset:512
	v_lshl_add_u64 v[52:53], v[52:53], 0, s[98:99]
	global_load_dwordx4 v[16:19], v[52:53], off offset:512
	v_lshl_add_u64 v[52:53], v[52:53], 0, s[98:99]
	global_load_dwordx4 v[20:23], v[52:53], off offset:512
	v_lshl_add_u64 v[52:53], v[52:53], 0, s[98:99]
	global_load_dwordx4 v[24:27], v[52:53], off offset:512
	v_lshl_add_u64 v[52:53], v[52:53], 0, s[98:99]
	global_load_dwordx4 v[28:31], v[52:53], off offset:512
	v_lshl_add_u64 v[52:53], v[52:53], 0, s[98:99]
	global_load_dwordx4 v[32:35], v[52:53], off offset:512
	v_lshl_add_u64 v[52:53], v[52:53], 0, s[98:99]
	global_load_dwordx4 v[36:39], v[52:53], off offset:512
	v_lshl_add_u64 v[52:53], v[52:53], 0, s[98:99]
	ds_read_b128 v[40:43], v67 offset:33792
	ds_read_b128 v[44:47], v67 offset:38016
	s_waitcnt vmcnt(7) lgkmcnt(1)
	v_pk_fma_f32 v[8:9], v[40:41], v[48:49], v[8:9]
	v_pk_fma_f32 v[10:11], v[42:43], v[50:51], v[10:11]
	global_store_dwordx4 v[54:55], v[8:11], off offset:512
	v_lshl_add_u64 v[54:55], v[54:55], 0, s[98:99]
	ds_read_b128 v[40:43], v67 offset:42240
	s_waitcnt vmcnt(7) lgkmcnt(1)
	v_pk_fma_f32 v[12:13], v[44:45], v[48:49], v[12:13]
	v_pk_fma_f32 v[14:15], v[46:47], v[50:51], v[14:15]
	global_store_dwordx4 v[54:55], v[12:15], off offset:512
	v_lshl_add_u64 v[54:55], v[54:55], 0, s[98:99]
	ds_read_b128 v[44:47], v67 offset:46464
	s_waitcnt vmcnt(7) lgkmcnt(1)
	v_pk_fma_f32 v[16:17], v[40:41], v[48:49], v[16:17]
	v_pk_fma_f32 v[18:19], v[42:43], v[50:51], v[18:19]
	global_store_dwordx4 v[54:55], v[16:19], off offset:512
	v_lshl_add_u64 v[54:55], v[54:55], 0, s[98:99]
	ds_read_b128 v[40:43], v67 offset:50688
	s_waitcnt vmcnt(7) lgkmcnt(1)
	v_pk_fma_f32 v[20:21], v[44:45], v[48:49], v[20:21]
	v_pk_fma_f32 v[22:23], v[46:47], v[50:51], v[22:23]
	global_store_dwordx4 v[54:55], v[20:23], off offset:512
	v_lshl_add_u64 v[54:55], v[54:55], 0, s[98:99]
	ds_read_b128 v[44:47], v67 offset:54912
	s_waitcnt vmcnt(7) lgkmcnt(1)
	v_pk_fma_f32 v[24:25], v[40:41], v[48:49], v[24:25]
	v_pk_fma_f32 v[26:27], v[42:43], v[50:51], v[26:27]
	global_store_dwordx4 v[54:55], v[24:27], off offset:512
	v_lshl_add_u64 v[54:55], v[54:55], 0, s[98:99]
	ds_read_b128 v[40:43], v67 offset:59136
	s_waitcnt vmcnt(7) lgkmcnt(1)
	v_pk_fma_f32 v[28:29], v[44:45], v[48:49], v[28:29]
	v_pk_fma_f32 v[30:31], v[46:47], v[50:51], v[30:31]
	global_store_dwordx4 v[54:55], v[28:31], off offset:512
	v_lshl_add_u64 v[54:55], v[54:55], 0, s[98:99]
	ds_read_b128 v[44:47], v67 offset:63360
	s_waitcnt vmcnt(7) lgkmcnt(1)
	v_pk_fma_f32 v[32:33], v[40:41], v[48:49], v[32:33]
	v_pk_fma_f32 v[34:35], v[42:43], v[50:51], v[34:35]
	global_store_dwordx4 v[54:55], v[32:35], off offset:512
	v_lshl_add_u64 v[54:55], v[54:55], 0, s[98:99]
	s_waitcnt vmcnt(7) lgkmcnt(0)
	v_pk_fma_f32 v[36:37], v[44:45], v[48:49], v[36:37]
	v_pk_fma_f32 v[38:39], v[46:47], v[50:51], v[38:39]
	global_store_dwordx4 v[54:55], v[36:39], off offset:512
	v_lshl_add_u64 v[54:55], v[54:55], 0, s[98:99]
	v_add_u32_e32 v67, 0x10800, v67
	s_mov_b32 s4, 0x80000
	s_mov_b32 s5, 0
	s_add_i32 s17, s17, s22
	s_cmpk_gt_i32 s17, 0xff
	s_barrier
	s_cbranch_scc0 .LBB0_742

.LBB0_1200:
	global_load_dwordx4 v[116:119], v[70:71], off
	v_lshl_add_u64 v[120:121], v[72:73], 0, s[12:13]
	v_lshl_add_u64 v[122:123], v[72:73], 0, s[12:13]
	s_mov_b32 s98, 0x8000
	s_mov_b32 s99, 0
	global_load_dwordx4 v[76:79], v[120:121], off
	v_lshl_add_u64 v[120:121], v[120:121], 0, s[98:99]
	global_load_dwordx4 v[80:83], v[120:121], off
	v_lshl_add_u64 v[120:121], v[120:121], 0, s[98:99]
	global_load_dwordx4 v[84:87], v[120:121], off
	v_lshl_add_u64 v[120:121], v[120:121], 0, s[98:99]
	global_load_dwordx4 v[88:91], v[120:121], off
	v_lshl_add_u64 v[120:121], v[120:121], 0, s[98:99]
	global_load_dwordx4 v[92:95], v[120:121], off
	v_lshl_add_u64 v[120:121], v[120:121], 0, s[98:99]
	global_load_dwordx4 v[96:99], v[120:121], off
	v_lshl_add_u64 v[120:121], v[120:121], 0, s[98:99]
	global_load_dwordx4 v[100:103], v[120:121], off
	v_lshl_add_u64 v[120:121], v[120:121], 0, s[98:99]
	global_load_dwordx4 v[104:107], v[120:121], off
	v_lshl_add_u64 v[120:121], v[120:121], 0, s[98:99]
	ds_read_b128 v[108:111], v65 offset:0
	ds_read_b128 v[112:115], v65 offset:4224
	s_waitcnt vmcnt(7) lgkmcnt(1)
	v_pk_fma_f32 v[76:77], v[108:109], v[116:117], v[76:77]
	v_pk_fma_f32 v[78:79], v[110:111], v[118:119], v[78:79]
	global_store_dwordx4 v[122:123], v[76:79], off
	v_lshl_add_u64 v[122:123], v[122:123], 0, s[98:99]
	ds_read_b128 v[108:111], v65 offset:8448
	s_waitcnt vmcnt(7) lgkmcnt(1)
	v_pk_fma_f32 v[80:81], v[112:113], v[116:117], v[80:81]
	v_pk_fma_f32 v[82:83], v[114:115], v[118:119], v[82:83]
	global_store_dwordx4 v[122:123], v[80:83], off
	v_lshl_add_u64 v[122:123], v[122:123], 0, s[98:99]
	ds_read_b128 v[112:115], v65 offset:12672
	s_waitcnt vmcnt(7) lgkmcnt(1)
	v_pk_fma_f32 v[84:85], v[108:109], v[116:117], v[84:85]
	v_pk_fma_f32 v[86:87], v[110:111], v[118:119], v[86:87]
	global_store_dwordx4 v[122:123], v[84:87], off
	v_lshl_add_u64 v[122:123], v[122:123], 0, s[98:99]
	ds_read_b128 v[108:111], v65 offset:16896
	s_waitcnt vmcnt(7) lgkmcnt(1)
	v_pk_fma_f32 v[88:89], v[112:113], v[116:117], v[88:89]
	v_pk_fma_f32 v[90:91], v[114:115], v[118:119], v[90:91]
	global_store_dwordx4 v[122:123], v[88:91], off
	v_lshl_add_u64 v[122:123], v[122:123], 0, s[98:99]
	ds_read_b128 v[112:115], v65 offset:21120
	s_waitcnt vmcnt(7) lgkmcnt(1)
	v_pk_fma_f32 v[92:93], v[108:109], v[116:117], v[92:93]
	v_pk_fma_f32 v[94:95], v[110:111], v[118:119], v[94:95]
	global_store_dwordx4 v[122:123], v[92:95], off
	v_lshl_add_u64 v[122:123], v[122:123], 0, s[98:99]
	ds_read_b128 v[108:111], v65 offset:25344
	s_waitcnt vmcnt(7) lgkmcnt(1)
	v_pk_fma_f32 v[96:97], v[112:113], v[116:117], v[96:97]
	v_pk_fma_f32 v[98:99], v[114:115], v[118:119], v[98:99]
	global_store_dwordx4 v[122:123], v[96:99], off
	v_lshl_add_u64 v[122:123], v[122:123], 0, s[98:99]
	ds_read_b128 v[112:115], v65 offset:29568
	s_waitcnt vmcnt(7) lgkmcnt(1)
	v_pk_fma_f32 v[100:101], v[108:109], v[116:117], v[100:101]
	v_pk_fma_f32 v[102:103], v[110:111], v[118:119], v[102:103]
	global_store_dwordx4 v[122:123], v[100:103], off
	v_lshl_add_u64 v[122:123], v[122:123], 0, s[98:99]
	s_waitcnt vmcnt(7) lgkmcnt(0)
	v_pk_fma_f32 v[104:105], v[112:113], v[116:117], v[104:105]
	v_pk_fma_f32 v[106:107], v[114:115], v[118:119], v[106:107]
	global_store_dwordx4 v[122:123], v[104:107], off
	v_lshl_add_u64 v[122:123], v[122:123], 0, s[98:99]
	global_load_dwordx4 v[76:79], v[120:121], off
	v_lshl_add_u64 v[120:121], v[120:121], 0, s[98:99]
	global_load_dwordx4 v[80:83], v[120:121], off
	v_lshl_add_u64 v[120:121], v[120:121], 0, s[98:99]
	global_load_dwordx4 v[84:87], v[120:121], off
	v_lshl_add_u64 v[120:121], v[120:121], 0, s[98:99]
	global_load_dwordx4 v[88:91], v[120:121], off
	v_lshl_add_u64 v[120:121], v[120:121], 0, s[98:99]
	global_load_dwordx4 v[92:95], v[120:121], off
	v_lshl_add_u64 v[120:121], v[120:121], 0, s[98:99]
	global_load_dwordx4 v[96:99], v[120:121], off
	v_lshl_add_u64 v[120:121], v[120:121], 0, s[98:99]
	global_load_dwordx4 v[100:103], v[120:121], off
	v_lshl_add_u64 v[120:121], v[120:121], 0, s[98:99]
	global_load_dwordx4 v[104:107], v[120:121], off
	v_lshl_add_u64 v[120:121], v[120:121], 0, s[98:99]
	ds_read_b128 v[108:111], v65 offset:33792
	ds_read_b128 v[112:115], v65 offset:38016
	s_waitcnt vmcnt(7) lgkmcnt(1)
	v_pk_fma_f32 v[76:77], v[108:109], v[116:117], v[76:77]
	v_pk_fma_f32 v[78:79], v[110:111], v[118:119], v[78:79]
	global_store_dwordx4 v[122:123], v[76:79], off
	v_lshl_add_u64 v[122:123], v[122:123], 0, s[98:99]
	ds_read_b128 v[108:111], v65 offset:42240
	s_waitcnt vmcnt(7) lgkmcnt(1)
	v_pk_fma_f32 v[80:81], v[112:113], v[116:117], v[80:81]
	v_pk_fma_f32 v[82:83], v[114:115], v[118:119], v[82:83]
	global_store_dwordx4 v[122:123], v[80:83], off
	v_lshl_add_u64 v[122:123], v[122:123], 0, s[98:99]
	ds_read_b128 v[112:115], v65 offset:46464
	s_waitcnt vmcnt(7) lgkmcnt(1)
	v_pk_fma_f32 v[84:85], v[108:109], v[116:117], v[84:85]
	v_pk_fma_f32 v[86:87], v[110:111], v[118:119], v[86:87]
	global_store_dwordx4 v[122:123], v[84:87], off
	v_lshl_add_u64 v[122:123], v[122:123], 0, s[98:99]
	ds_read_b128 v[108:111], v65 offset:50688
	s_waitcnt vmcnt(7) lgkmcnt(1)
	v_pk_fma_f32 v[88:89], v[112:113], v[116:117], v[88:89]
	v_pk_fma_f32 v[90:91], v[114:115], v[118:119], v[90:91]
	global_store_dwordx4 v[122:123], v[88:91], off
	v_lshl_add_u64 v[122:123], v[122:123], 0, s[98:99]
	ds_read_b128 v[112:115], v65 offset:54912
	s_waitcnt vmcnt(7) lgkmcnt(1)
	v_pk_fma_f32 v[92:93], v[108:109], v[116:117], v[92:93]
	v_pk_fma_f32 v[94:95], v[110:111], v[118:119], v[94:95]
	global_store_dwordx4 v[122:123], v[92:95], off
	v_lshl_add_u64 v[122:123], v[122:123], 0, s[98:99]
	ds_read_b128 v[108:111], v65 offset:59136
	s_waitcnt vmcnt(7) lgkmcnt(1)
	v_pk_fma_f32 v[96:97], v[112:113], v[116:117], v[96:97]
	v_pk_fma_f32 v[98:99], v[114:115], v[118:119], v[98:99]
	global_store_dwordx4 v[122:123], v[96:99], off
	v_lshl_add_u64 v[122:123], v[122:123], 0, s[98:99]
	ds_read_b128 v[112:115], v65 offset:63360
	s_waitcnt vmcnt(7) lgkmcnt(1)
	v_pk_fma_f32 v[100:101], v[108:109], v[116:117], v[100:101]
	v_pk_fma_f32 v[102:103], v[110:111], v[118:119], v[102:103]
	global_store_dwordx4 v[122:123], v[100:103], off
	v_lshl_add_u64 v[122:123], v[122:123], 0, s[98:99]
	s_waitcnt vmcnt(7) lgkmcnt(0)
	v_pk_fma_f32 v[104:105], v[112:113], v[116:117], v[104:105]
	v_pk_fma_f32 v[106:107], v[114:115], v[118:119], v[106:107]
	global_store_dwordx4 v[122:123], v[104:107], off
	v_lshl_add_u64 v[122:123], v[122:123], 0, s[98:99]
	v_add_u32_e32 v65, 0x10800, v65
	s_mov_b32 s12, 0x80000
	s_mov_b32 s13, 0
	s_barrier
	ds_write_b128 v141, v[60:63]
	ds_write_b128 v141, v[48:51] offset:64
	ds_write_b128 v141, v[44:47] offset:8448
	ds_write_b128 v141, v[40:43] offset:8512
	ds_write_b128 v141, v[36:39] offset:16896
	ds_write_b128 v141, v[32:35] offset:16960
	ds_write_b128 v141, v[28:31] offset:25344
	ds_write_b128 v141, v[24:27] offset:25408
	ds_write_b128 v141, v[20:23] offset:33792
	ds_write_b128 v141, v[16:19] offset:33856
	ds_write_b128 v141, v[12:15] offset:42240
	ds_write_b128 v141, v[8:11] offset:42304
	ds_write_b128 v141, v[4:7] offset:50688
	ds_write_b128 v141, v[0:3] offset:50752
	ds_write_b128 v141, v[52:55] offset:59136
	ds_write_b128 v141, v[56:59] offset:59200
	s_waitcnt lgkmcnt(0)
	s_barrier
	s_and_saveexec_b64 s[12:13], s[6:7]
	s_xor_b64 s[6:7], exec, s[12:13]
	v_add_u32_e32 v136, 0xffffc000, v64
	v_lshlrev_b64 v[0:1], 12, v[136:137]
	v_lshl_add_u64 v[2:3], s[70:71], 0, v[0:1]
	s_or_saveexec_b64 s[6:7], s[6:7]
	v_mov_b64_e32 v[0:1], 0xc000
	s_xor_b64 exec, exec, s[6:7]
	v_ashrrev_i32_e32 v65, 31, v64
	v_lshlrev_b64 v[0:1], 12, v[64:65]
	v_lshl_add_u64 v[2:3], s[84:85], 0, v[0:1]
	v_ashrrev_i32_e32 v0, 11, v64
	v_mul_hi_i32_i24_e32 v1, 0x1800, v0
	v_mul_i32_i24_e32 v0, 0x1800, v0
	s_or_b64 exec, exec, s[6:7]
	v_lshl_add_u64 v[0:1], v[0:1], 2, s[0:1]
	v_lshl_add_u64 v[0:1], s[10:11], 2, v[0:1]
	v_lshlrev_b32_e32 v136, 2, v66
	v_lshl_add_u64 v[0:1], v[0:1], 0, v[136:137]
	v_lshl_add_u64 v[2:3], v[2:3], 0, v[68:69]
	s_mov_b64 s[6:7], 0
.LBB0_1206:
	global_load_dwordx4 v[48:51], v[0:1], off offset:512
	v_lshl_add_u64 v[52:53], v[2:3], 0, s[6:7]
	v_lshl_add_u64 v[54:55], v[2:3], 0, s[6:7]
	s_mov_b32 s98, 0x8000
	s_mov_b32 s99, 0
	global_load_dwordx4 v[8:11], v[52:53], off offset:512
	v_lshl_add_u64 v[52:53], v[52:53], 0, s[98:99]
	global_load_dwordx4 v[12:15], v[52:53], off offset:512
	v_lshl_add_u64 v[52:53], v[52:53], 0, s[98:99]
	global_load_dwordx4 v[16:19], v[52:53], off offset:512
	v_lshl_add_u64 v[52:53], v[52:53], 0, s[98:99]
	global_load_dwordx4 v[20:23], v[52:53], off offset:512
	v_lshl_add_u64 v[52:53], v[52:53], 0, s[98:99]
	global_load_dwordx4 v[24:27], v[52:53], off offset:512
	v_lshl_add_u64 v[52:53], v[52:53], 0, s[98:99]
	global_load_dwordx4 v[28:31], v[52:53], off offset:512
	v_lshl_add_u64 v[52:53], v[52:53], 0, s[98:99]
	global_load_dwordx4 v[32:35], v[52:53], off offset:512
	v_lshl_add_u64 v[52:53], v[52:53], 0, s[98:99]
	global_load_dwordx4 v[36:39], v[52:53], off offset:512
	v_lshl_add_u64 v[52:53], v[52:53], 0, s[98:99]
	ds_read_b128 v[40:43], v67 offset:0
	ds_read_b128 v[44:47], v67 offset:4224
	s_waitcnt vmcnt(7) lgkmcnt(1)
	v_pk_fma_f32 v[8:9], v[40:41], v[48:49], v[8:9]
	v_pk_fma_f32 v[10:11], v[42:43], v[50:51], v[10:11]
	global_store_dwordx4 v[54:55], v[8:11], off offset:512
	v_lshl_add_u64 v[54:55], v[54:55], 0, s[98:99]
	ds_read_b128 v[40:43], v67 offset:8448
	s_waitcnt vmcnt(7) lgkmcnt(1)
	v_pk_fma_f32 v[12:13], v[44:45], v[48:49], v[12:13]
	v_pk_fma_f32 v[14:15], v[46:47], v[50:51], v[14:15]
	global_store_dwordx4 v[54:55], v[12:15], off offset:512
	v_lshl_add_u64 v[54:55], v[54:55], 0, s[98:99]
	ds_read_b128 v[44:47], v67 offset:12672
	s_waitcnt vmcnt(7) lgkmcnt(1)
	v_pk_fma_f32 v[16:17], v[40:41], v[48:49], v[16:17]
	v_pk_fma_f32 v[18:19], v[42:43], v[50:51], v[18:19]
	global_store_dwordx4 v[54:55], v[16:19], off offset:512
	v_lshl_add_u64 v[54:55], v[54:55], 0, s[98:99]
	ds_read_b128 v[40:43], v67 offset:16896
	s_waitcnt vmcnt(7) lgkmcnt(1)
	v_pk_fma_f32 v[20:21], v[44:45], v[48:49], v[20:21]
	v_pk_fma_f32 v[22:23], v[46:47], v[50:51], v[22:23]
	global_store_dwordx4 v[54:55], v[20:23], off offset:512
	v_lshl_add_u64 v[54:55], v[54:55], 0, s[98:99]
	ds_read_b128 v[44:47], v67 offset:21120
	s_waitcnt vmcnt(7) lgkmcnt(1)
	v_pk_fma_f32 v[24:25], v[40:41], v[48:49], v[24:25]
	v_pk_fma_f32 v[26:27], v[42:43], v[50:51], v[26:27]
	global_store_dwordx4 v[54:55], v[24:27], off offset:512
	v_lshl_add_u64 v[54:55], v[54:55], 0, s[98:99]
	ds_read_b128 v[40:43], v67 offset:25344
	s_waitcnt vmcnt(7) lgkmcnt(1)
	v_pk_fma_f32 v[28:29], v[44:45], v[48:49], v[28:29]
	v_pk_fma_f32 v[30:31], v[46:47], v[50:51], v[30:31]
	global_store_dwordx4 v[54:55], v[28:31], off offset:512
	v_lshl_add_u64 v[54:55], v[54:55], 0, s[98:99]
	ds_read_b128 v[44:47], v67 offset:29568
	s_waitcnt vmcnt(7) lgkmcnt(1)
	v_pk_fma_f32 v[32:33], v[40:41], v[48:49], v[32:33]
	v_pk_fma_f32 v[34:35], v[42:43], v[50:51], v[34:35]
	global_store_dwordx4 v[54:55], v[32:35], off offset:512
	v_lshl_add_u64 v[54:55], v[54:55], 0, s[98:99]
	s_waitcnt vmcnt(7) lgkmcnt(0)
	v_pk_fma_f32 v[36:37], v[44:45], v[48:49], v[36:37]
	v_pk_fma_f32 v[38:39], v[46:47], v[50:51], v[38:39]
	global_store_dwordx4 v[54:55], v[36:39], off offset:512
	v_lshl_add_u64 v[54:55], v[54:55], 0, s[98:99]
	global_load_dwordx4 v[8:11], v[52:53], off offset:512
	v_lshl_add_u64 v[52:53], v[52:53], 0, s[98:99]
	global_load_dwordx4 v[12:15], v[52:53], off offset:512
	v_lshl_add_u64 v[52:53], v[52:53], 0, s[98:99]
	global_load_dwordx4 v[16:19], v[52:53], off offset:512
	v_lshl_add_u64 v[52:53], v[52:53], 0, s[98:99]
	global_load_dwordx4 v[20:23], v[52:53], off offset:512
	v_lshl_add_u64 v[52:53], v[52:53], 0, s[98:99]
	global_load_dwordx4 v[24:27], v[52:53], off offset:512
	v_lshl_add_u64 v[52:53], v[52:53], 0, s[98:99]
	global_load_dwordx4 v[28:31], v[52:53], off offset:512
	v_lshl_add_u64 v[52:53], v[52:53], 0, s[98:99]
	global_load_dwordx4 v[32:35], v[52:53], off offset:512
	v_lshl_add_u64 v[52:53], v[52:53], 0, s[98:99]
	global_load_dwordx4 v[36:39], v[52:53], off offset:512
	v_lshl_add_u64 v[52:53], v[52:53], 0, s[98:99]
	ds_read_b128 v[40:43], v67 offset:33792
	ds_read_b128 v[44:47], v67 offset:38016
	s_waitcnt vmcnt(7) lgkmcnt(1)
	v_pk_fma_f32 v[8:9], v[40:41], v[48:49], v[8:9]
	v_pk_fma_f32 v[10:11], v[42:43], v[50:51], v[10:11]
	global_store_dwordx4 v[54:55], v[8:11], off offset:512
	v_lshl_add_u64 v[54:55], v[54:55], 0, s[98:99]
	ds_read_b128 v[40:43], v67 offset:42240
	s_waitcnt vmcnt(7) lgkmcnt(1)
	v_pk_fma_f32 v[12:13], v[44:45], v[48:49], v[12:13]
	v_pk_fma_f32 v[14:15], v[46:47], v[50:51], v[14:15]
	global_store_dwordx4 v[54:55], v[12:15], off offset:512
	v_lshl_add_u64 v[54:55], v[54:55], 0, s[98:99]
	ds_read_b128 v[44:47], v67 offset:46464
	s_waitcnt vmcnt(7) lgkmcnt(1)
	v_pk_fma_f32 v[16:17], v[40:41], v[48:49], v[16:17]
	v_pk_fma_f32 v[18:19], v[42:43], v[50:51], v[18:19]
	global_store_dwordx4 v[54:55], v[16:19], off offset:512
	v_lshl_add_u64 v[54:55], v[54:55], 0, s[98:99]
	ds_read_b128 v[40:43], v67 offset:50688
	s_waitcnt vmcnt(7) lgkmcnt(1)
	v_pk_fma_f32 v[20:21], v[44:45], v[48:49], v[20:21]
	v_pk_fma_f32 v[22:23], v[46:47], v[50:51], v[22:23]
	global_store_dwordx4 v[54:55], v[20:23], off offset:512
	v_lshl_add_u64 v[54:55], v[54:55], 0, s[98:99]
	ds_read_b128 v[44:47], v67 offset:54912
	s_waitcnt vmcnt(7) lgkmcnt(1)
	v_pk_fma_f32 v[24:25], v[40:41], v[48:49], v[24:25]
	v_pk_fma_f32 v[26:27], v[42:43], v[50:51], v[26:27]
	global_store_dwordx4 v[54:55], v[24:27], off offset:512
	v_lshl_add_u64 v[54:55], v[54:55], 0, s[98:99]
	ds_read_b128 v[40:43], v67 offset:59136
	s_waitcnt vmcnt(7) lgkmcnt(1)
	v_pk_fma_f32 v[28:29], v[44:45], v[48:49], v[28:29]
	v_pk_fma_f32 v[30:31], v[46:47], v[50:51], v[30:31]
	global_store_dwordx4 v[54:55], v[28:31], off offset:512
	v_lshl_add_u64 v[54:55], v[54:55], 0, s[98:99]
	ds_read_b128 v[44:47], v67 offset:63360
	s_waitcnt vmcnt(7) lgkmcnt(1)
	v_pk_fma_f32 v[32:33], v[40:41], v[48:49], v[32:33]
	v_pk_fma_f32 v[34:35], v[42:43], v[50:51], v[34:35]
	global_store_dwordx4 v[54:55], v[32:35], off offset:512
	v_lshl_add_u64 v[54:55], v[54:55], 0, s[98:99]
	s_waitcnt vmcnt(7) lgkmcnt(0)
	v_pk_fma_f32 v[36:37], v[44:45], v[48:49], v[36:37]
	v_pk_fma_f32 v[38:39], v[46:47], v[50:51], v[38:39]
	global_store_dwordx4 v[54:55], v[36:39], off offset:512
	v_lshl_add_u64 v[54:55], v[54:55], 0, s[98:99]
	v_add_u32_e32 v67, 0x10800, v67
	s_mov_b32 s6, 0x80000
	s_mov_b32 s7, 0
	s_add_i32 s17, s17, s22
	s_cmpk_gt_i32 s17, 0xff
	s_barrier
	s_cbranch_scc0 .LBB0_1191

.LBB0_1866:
	global_load_dwordx4 v[116:119], v[70:71], off
	v_lshl_add_u64 v[120:121], v[72:73], 0, s[14:15]
	v_lshl_add_u64 v[122:123], v[72:73], 0, s[14:15]
	s_mov_b32 s98, 0x8000
	s_mov_b32 s99, 0
	global_load_dwordx4 v[76:79], v[120:121], off
	v_lshl_add_u64 v[120:121], v[120:121], 0, s[98:99]
	global_load_dwordx4 v[80:83], v[120:121], off
	v_lshl_add_u64 v[120:121], v[120:121], 0, s[98:99]
	global_load_dwordx4 v[84:87], v[120:121], off
	v_lshl_add_u64 v[120:121], v[120:121], 0, s[98:99]
	global_load_dwordx4 v[88:91], v[120:121], off
	v_lshl_add_u64 v[120:121], v[120:121], 0, s[98:99]
	global_load_dwordx4 v[92:95], v[120:121], off
	v_lshl_add_u64 v[120:121], v[120:121], 0, s[98:99]
	global_load_dwordx4 v[96:99], v[120:121], off
	v_lshl_add_u64 v[120:121], v[120:121], 0, s[98:99]
	global_load_dwordx4 v[100:103], v[120:121], off
	v_lshl_add_u64 v[120:121], v[120:121], 0, s[98:99]
	global_load_dwordx4 v[104:107], v[120:121], off
	v_lshl_add_u64 v[120:121], v[120:121], 0, s[98:99]
	ds_read_b128 v[108:111], v65 offset:0
	ds_read_b128 v[112:115], v65 offset:4224
	s_waitcnt vmcnt(7) lgkmcnt(1)
	v_pk_fma_f32 v[76:77], v[108:109], v[116:117], v[76:77]
	v_pk_fma_f32 v[78:79], v[110:111], v[118:119], v[78:79]
	global_store_dwordx4 v[122:123], v[76:79], off
	v_lshl_add_u64 v[122:123], v[122:123], 0, s[98:99]
	ds_read_b128 v[108:111], v65 offset:8448
	s_waitcnt vmcnt(7) lgkmcnt(1)
	v_pk_fma_f32 v[80:81], v[112:113], v[116:117], v[80:81]
	v_pk_fma_f32 v[82:83], v[114:115], v[118:119], v[82:83]
	global_store_dwordx4 v[122:123], v[80:83], off
	v_lshl_add_u64 v[122:123], v[122:123], 0, s[98:99]
	ds_read_b128 v[112:115], v65 offset:12672
	s_waitcnt vmcnt(7) lgkmcnt(1)
	v_pk_fma_f32 v[84:85], v[108:109], v[116:117], v[84:85]
	v_pk_fma_f32 v[86:87], v[110:111], v[118:119], v[86:87]
	global_store_dwordx4 v[122:123], v[84:87], off
	v_lshl_add_u64 v[122:123], v[122:123], 0, s[98:99]
	ds_read_b128 v[108:111], v65 offset:16896
	s_waitcnt vmcnt(7) lgkmcnt(1)
	v_pk_fma_f32 v[88:89], v[112:113], v[116:117], v[88:89]
	v_pk_fma_f32 v[90:91], v[114:115], v[118:119], v[90:91]
	global_store_dwordx4 v[122:123], v[88:91], off
	v_lshl_add_u64 v[122:123], v[122:123], 0, s[98:99]
	ds_read_b128 v[112:115], v65 offset:21120
	s_waitcnt vmcnt(7) lgkmcnt(1)
	v_pk_fma_f32 v[92:93], v[108:109], v[116:117], v[92:93]
	v_pk_fma_f32 v[94:95], v[110:111], v[118:119], v[94:95]
	global_store_dwordx4 v[122:123], v[92:95], off
	v_lshl_add_u64 v[122:123], v[122:123], 0, s[98:99]
	ds_read_b128 v[108:111], v65 offset:25344
	s_waitcnt vmcnt(7) lgkmcnt(1)
	v_pk_fma_f32 v[96:97], v[112:113], v[116:117], v[96:97]
	v_pk_fma_f32 v[98:99], v[114:115], v[118:119], v[98:99]
	global_store_dwordx4 v[122:123], v[96:99], off
	v_lshl_add_u64 v[122:123], v[122:123], 0, s[98:99]
	ds_read_b128 v[112:115], v65 offset:29568
	s_waitcnt vmcnt(7) lgkmcnt(1)
	v_pk_fma_f32 v[100:101], v[108:109], v[116:117], v[100:101]
	v_pk_fma_f32 v[102:103], v[110:111], v[118:119], v[102:103]
	global_store_dwordx4 v[122:123], v[100:103], off
	v_lshl_add_u64 v[122:123], v[122:123], 0, s[98:99]
	s_waitcnt vmcnt(7) lgkmcnt(0)
	v_pk_fma_f32 v[104:105], v[112:113], v[116:117], v[104:105]
	v_pk_fma_f32 v[106:107], v[114:115], v[118:119], v[106:107]
	global_store_dwordx4 v[122:123], v[104:107], off
	v_lshl_add_u64 v[122:123], v[122:123], 0, s[98:99]
	global_load_dwordx4 v[76:79], v[120:121], off
	v_lshl_add_u64 v[120:121], v[120:121], 0, s[98:99]
	global_load_dwordx4 v[80:83], v[120:121], off
	v_lshl_add_u64 v[120:121], v[120:121], 0, s[98:99]
	global_load_dwordx4 v[84:87], v[120:121], off
	v_lshl_add_u64 v[120:121], v[120:121], 0, s[98:99]
	global_load_dwordx4 v[88:91], v[120:121], off
	v_lshl_add_u64 v[120:121], v[120:121], 0, s[98:99]
	global_load_dwordx4 v[92:95], v[120:121], off
	v_lshl_add_u64 v[120:121], v[120:121], 0, s[98:99]
	global_load_dwordx4 v[96:99], v[120:121], off
	v_lshl_add_u64 v[120:121], v[120:121], 0, s[98:99]
	global_load_dwordx4 v[100:103], v[120:121], off
	v_lshl_add_u64 v[120:121], v[120:121], 0, s[98:99]
	global_load_dwordx4 v[104:107], v[120:121], off
	v_lshl_add_u64 v[120:121], v[120:121], 0, s[98:99]
	ds_read_b128 v[108:111], v65 offset:33792
	ds_read_b128 v[112:115], v65 offset:38016
	s_waitcnt vmcnt(7) lgkmcnt(1)
	v_pk_fma_f32 v[76:77], v[108:109], v[116:117], v[76:77]
	v_pk_fma_f32 v[78:79], v[110:111], v[118:119], v[78:79]
	global_store_dwordx4 v[122:123], v[76:79], off
	v_lshl_add_u64 v[122:123], v[122:123], 0, s[98:99]
	ds_read_b128 v[108:111], v65 offset:42240
	s_waitcnt vmcnt(7) lgkmcnt(1)
	v_pk_fma_f32 v[80:81], v[112:113], v[116:117], v[80:81]
	v_pk_fma_f32 v[82:83], v[114:115], v[118:119], v[82:83]
	global_store_dwordx4 v[122:123], v[80:83], off
	v_lshl_add_u64 v[122:123], v[122:123], 0, s[98:99]
	ds_read_b128 v[112:115], v65 offset:46464
	s_waitcnt vmcnt(7) lgkmcnt(1)
	v_pk_fma_f32 v[84:85], v[108:109], v[116:117], v[84:85]
	v_pk_fma_f32 v[86:87], v[110:111], v[118:119], v[86:87]
	global_store_dwordx4 v[122:123], v[84:87], off
	v_lshl_add_u64 v[122:123], v[122:123], 0, s[98:99]
	ds_read_b128 v[108:111], v65 offset:50688
	s_waitcnt vmcnt(7) lgkmcnt(1)
	v_pk_fma_f32 v[88:89], v[112:113], v[116:117], v[88:89]
	v_pk_fma_f32 v[90:91], v[114:115], v[118:119], v[90:91]
	global_store_dwordx4 v[122:123], v[88:91], off
	v_lshl_add_u64 v[122:123], v[122:123], 0, s[98:99]
	ds_read_b128 v[112:115], v65 offset:54912
	s_waitcnt vmcnt(7) lgkmcnt(1)
	v_pk_fma_f32 v[92:93], v[108:109], v[116:117], v[92:93]
	v_pk_fma_f32 v[94:95], v[110:111], v[118:119], v[94:95]
	global_store_dwordx4 v[122:123], v[92:95], off
	v_lshl_add_u64 v[122:123], v[122:123], 0, s[98:99]
	ds_read_b128 v[108:111], v65 offset:59136
	s_waitcnt vmcnt(7) lgkmcnt(1)
	v_pk_fma_f32 v[96:97], v[112:113], v[116:117], v[96:97]
	v_pk_fma_f32 v[98:99], v[114:115], v[118:119], v[98:99]
	global_store_dwordx4 v[122:123], v[96:99], off
	v_lshl_add_u64 v[122:123], v[122:123], 0, s[98:99]
	ds_read_b128 v[112:115], v65 offset:63360
	s_waitcnt vmcnt(7) lgkmcnt(1)
	v_pk_fma_f32 v[100:101], v[108:109], v[116:117], v[100:101]
	v_pk_fma_f32 v[102:103], v[110:111], v[118:119], v[102:103]
	global_store_dwordx4 v[122:123], v[100:103], off
	v_lshl_add_u64 v[122:123], v[122:123], 0, s[98:99]
	s_waitcnt vmcnt(7) lgkmcnt(0)
	v_pk_fma_f32 v[104:105], v[112:113], v[116:117], v[104:105]
	v_pk_fma_f32 v[106:107], v[114:115], v[118:119], v[106:107]
	global_store_dwordx4 v[122:123], v[104:107], off
	v_lshl_add_u64 v[122:123], v[122:123], 0, s[98:99]
	v_add_u32_e32 v65, 0x10800, v65
	s_mov_b32 s14, 0x80000
	s_mov_b32 s15, 0
	s_barrier
	ds_write_b128 v149, v[60:63]
	ds_write_b128 v149, v[48:51] offset:64
	ds_write_b128 v149, v[44:47] offset:8448
	ds_write_b128 v149, v[40:43] offset:8512
	ds_write_b128 v149, v[36:39] offset:16896
	ds_write_b128 v149, v[32:35] offset:16960
	ds_write_b128 v149, v[28:31] offset:25344
	ds_write_b128 v149, v[24:27] offset:25408
	ds_write_b128 v149, v[20:23] offset:33792
	ds_write_b128 v149, v[16:19] offset:33856
	ds_write_b128 v149, v[12:15] offset:42240
	ds_write_b128 v149, v[8:11] offset:42304
	ds_write_b128 v149, v[4:7] offset:50688
	ds_write_b128 v149, v[0:3] offset:50752
	ds_write_b128 v149, v[52:55] offset:59136
	ds_write_b128 v149, v[56:59] offset:59200
	s_waitcnt lgkmcnt(0)
	s_barrier
	s_and_saveexec_b64 s[14:15], s[0:1]
	s_xor_b64 s[0:1], exec, s[14:15]
	v_add_u32_e32 v138, 0xffffc000, v64
	v_lshlrev_b64 v[0:1], 12, v[138:139]
	v_lshl_add_u64 v[2:3], s[70:71], 0, v[0:1]
	s_or_saveexec_b64 s[0:1], s[0:1]
	v_mov_b64_e32 v[0:1], 0xc000
	s_xor_b64 exec, exec, s[0:1]
	v_ashrrev_i32_e32 v65, 31, v64
	v_lshlrev_b64 v[0:1], 12, v[64:65]
	v_lshl_add_u64 v[2:3], s[84:85], 0, v[0:1]
	v_ashrrev_i32_e32 v0, 11, v64
	v_mul_hi_i32_i24_e32 v1, 0x1800, v0
	v_mul_i32_i24_e32 v0, 0x1800, v0
	s_or_b64 exec, exec, s[0:1]
	v_lshl_add_u64 v[0:1], v[0:1], 2, s[6:7]
	v_lshl_add_u64 v[0:1], s[12:13], 2, v[0:1]
	v_lshlrev_b32_e32 v138, 2, v66
	v_lshl_add_u64 v[0:1], v[0:1], 0, v[138:139]
	v_lshl_add_u64 v[2:3], v[2:3], 0, v[68:69]
	s_mov_b64 s[0:1], 0
.LBB0_1872:
	global_load_dwordx4 v[48:51], v[0:1], off offset:512
	v_lshl_add_u64 v[52:53], v[2:3], 0, s[0:1]
	v_lshl_add_u64 v[54:55], v[2:3], 0, s[0:1]
	s_mov_b32 s98, 0x8000
	s_mov_b32 s99, 0
	global_load_dwordx4 v[8:11], v[52:53], off offset:512
	v_lshl_add_u64 v[52:53], v[52:53], 0, s[98:99]
	global_load_dwordx4 v[12:15], v[52:53], off offset:512
	v_lshl_add_u64 v[52:53], v[52:53], 0, s[98:99]
	global_load_dwordx4 v[16:19], v[52:53], off offset:512
	v_lshl_add_u64 v[52:53], v[52:53], 0, s[98:99]
	global_load_dwordx4 v[20:23], v[52:53], off offset:512
	v_lshl_add_u64 v[52:53], v[52:53], 0, s[98:99]
	global_load_dwordx4 v[24:27], v[52:53], off offset:512
	v_lshl_add_u64 v[52:53], v[52:53], 0, s[98:99]
	global_load_dwordx4 v[28:31], v[52:53], off offset:512
	v_lshl_add_u64 v[52:53], v[52:53], 0, s[98:99]
	global_load_dwordx4 v[32:35], v[52:53], off offset:512
	v_lshl_add_u64 v[52:53], v[52:53], 0, s[98:99]
	global_load_dwordx4 v[36:39], v[52:53], off offset:512
	v_lshl_add_u64 v[52:53], v[52:53], 0, s[98:99]
	ds_read_b128 v[40:43], v67 offset:0
	ds_read_b128 v[44:47], v67 offset:4224
	s_waitcnt vmcnt(7) lgkmcnt(1)
	v_pk_fma_f32 v[8:9], v[40:41], v[48:49], v[8:9]
	v_pk_fma_f32 v[10:11], v[42:43], v[50:51], v[10:11]
	global_store_dwordx4 v[54:55], v[8:11], off offset:512
	v_lshl_add_u64 v[54:55], v[54:55], 0, s[98:99]
	ds_read_b128 v[40:43], v67 offset:8448
	s_waitcnt vmcnt(7) lgkmcnt(1)
	v_pk_fma_f32 v[12:13], v[44:45], v[48:49], v[12:13]
	v_pk_fma_f32 v[14:15], v[46:47], v[50:51], v[14:15]
	global_store_dwordx4 v[54:55], v[12:15], off offset:512
	v_lshl_add_u64 v[54:55], v[54:55], 0, s[98:99]
	ds_read_b128 v[44:47], v67 offset:12672
	s_waitcnt vmcnt(7) lgkmcnt(1)
	v_pk_fma_f32 v[16:17], v[40:41], v[48:49], v[16:17]
	v_pk_fma_f32 v[18:19], v[42:43], v[50:51], v[18:19]
	global_store_dwordx4 v[54:55], v[16:19], off offset:512
	v_lshl_add_u64 v[54:55], v[54:55], 0, s[98:99]
	ds_read_b128 v[40:43], v67 offset:16896
	s_waitcnt vmcnt(7) lgkmcnt(1)
	v_pk_fma_f32 v[20:21], v[44:45], v[48:49], v[20:21]
	v_pk_fma_f32 v[22:23], v[46:47], v[50:51], v[22:23]
	global_store_dwordx4 v[54:55], v[20:23], off offset:512
	v_lshl_add_u64 v[54:55], v[54:55], 0, s[98:99]
	ds_read_b128 v[44:47], v67 offset:21120
	s_waitcnt vmcnt(7) lgkmcnt(1)
	v_pk_fma_f32 v[24:25], v[40:41], v[48:49], v[24:25]
	v_pk_fma_f32 v[26:27], v[42:43], v[50:51], v[26:27]
	global_store_dwordx4 v[54:55], v[24:27], off offset:512
	v_lshl_add_u64 v[54:55], v[54:55], 0, s[98:99]
	ds_read_b128 v[40:43], v67 offset:25344
	s_waitcnt vmcnt(7) lgkmcnt(1)
	v_pk_fma_f32 v[28:29], v[44:45], v[48:49], v[28:29]
	v_pk_fma_f32 v[30:31], v[46:47], v[50:51], v[30:31]
	global_store_dwordx4 v[54:55], v[28:31], off offset:512
	v_lshl_add_u64 v[54:55], v[54:55], 0, s[98:99]
	ds_read_b128 v[44:47], v67 offset:29568
	s_waitcnt vmcnt(7) lgkmcnt(1)
	v_pk_fma_f32 v[32:33], v[40:41], v[48:49], v[32:33]
	v_pk_fma_f32 v[34:35], v[42:43], v[50:51], v[34:35]
	global_store_dwordx4 v[54:55], v[32:35], off offset:512
	v_lshl_add_u64 v[54:55], v[54:55], 0, s[98:99]
	s_waitcnt vmcnt(7) lgkmcnt(0)
	v_pk_fma_f32 v[36:37], v[44:45], v[48:49], v[36:37]
	v_pk_fma_f32 v[38:39], v[46:47], v[50:51], v[38:39]
	global_store_dwordx4 v[54:55], v[36:39], off offset:512
	v_lshl_add_u64 v[54:55], v[54:55], 0, s[98:99]
	global_load_dwordx4 v[8:11], v[52:53], off offset:512
	v_lshl_add_u64 v[52:53], v[52:53], 0, s[98:99]
	global_load_dwordx4 v[12:15], v[52:53], off offset:512
	v_lshl_add_u64 v[52:53], v[52:53], 0, s[98:99]
	global_load_dwordx4 v[16:19], v[52:53], off offset:512
	v_lshl_add_u64 v[52:53], v[52:53], 0, s[98:99]
	global_load_dwordx4 v[20:23], v[52:53], off offset:512
	v_lshl_add_u64 v[52:53], v[52:53], 0, s[98:99]
	global_load_dwordx4 v[24:27], v[52:53], off offset:512
	v_lshl_add_u64 v[52:53], v[52:53], 0, s[98:99]
	global_load_dwordx4 v[28:31], v[52:53], off offset:512
	v_lshl_add_u64 v[52:53], v[52:53], 0, s[98:99]
	global_load_dwordx4 v[32:35], v[52:53], off offset:512
	v_lshl_add_u64 v[52:53], v[52:53], 0, s[98:99]
	global_load_dwordx4 v[36:39], v[52:53], off offset:512
	v_lshl_add_u64 v[52:53], v[52:53], 0, s[98:99]
	ds_read_b128 v[40:43], v67 offset:33792
	ds_read_b128 v[44:47], v67 offset:38016
	s_waitcnt vmcnt(7) lgkmcnt(1)
	v_pk_fma_f32 v[8:9], v[40:41], v[48:49], v[8:9]
	v_pk_fma_f32 v[10:11], v[42:43], v[50:51], v[10:11]
	global_store_dwordx4 v[54:55], v[8:11], off offset:512
	v_lshl_add_u64 v[54:55], v[54:55], 0, s[98:99]
	ds_read_b128 v[40:43], v67 offset:42240
	s_waitcnt vmcnt(7) lgkmcnt(1)
	v_pk_fma_f32 v[12:13], v[44:45], v[48:49], v[12:13]
	v_pk_fma_f32 v[14:15], v[46:47], v[50:51], v[14:15]
	global_store_dwordx4 v[54:55], v[12:15], off offset:512
	v_lshl_add_u64 v[54:55], v[54:55], 0, s[98:99]
	ds_read_b128 v[44:47], v67 offset:46464
	s_waitcnt vmcnt(7) lgkmcnt(1)
	v_pk_fma_f32 v[16:17], v[40:41], v[48:49], v[16:17]
	v_pk_fma_f32 v[18:19], v[42:43], v[50:51], v[18:19]
	global_store_dwordx4 v[54:55], v[16:19], off offset:512
	v_lshl_add_u64 v[54:55], v[54:55], 0, s[98:99]
	ds_read_b128 v[40:43], v67 offset:50688
	s_waitcnt vmcnt(7) lgkmcnt(1)
	v_pk_fma_f32 v[20:21], v[44:45], v[48:49], v[20:21]
	v_pk_fma_f32 v[22:23], v[46:47], v[50:51], v[22:23]
	global_store_dwordx4 v[54:55], v[20:23], off offset:512
	v_lshl_add_u64 v[54:55], v[54:55], 0, s[98:99]
	ds_read_b128 v[44:47], v67 offset:54912
	s_waitcnt vmcnt(7) lgkmcnt(1)
	v_pk_fma_f32 v[24:25], v[40:41], v[48:49], v[24:25]
	v_pk_fma_f32 v[26:27], v[42:43], v[50:51], v[26:27]
	global_store_dwordx4 v[54:55], v[24:27], off offset:512
	v_lshl_add_u64 v[54:55], v[54:55], 0, s[98:99]
	ds_read_b128 v[40:43], v67 offset:59136
	s_waitcnt vmcnt(7) lgkmcnt(1)
	v_pk_fma_f32 v[28:29], v[44:45], v[48:49], v[28:29]
	v_pk_fma_f32 v[30:31], v[46:47], v[50:51], v[30:31]
	global_store_dwordx4 v[54:55], v[28:31], off offset:512
	v_lshl_add_u64 v[54:55], v[54:55], 0, s[98:99]
	ds_read_b128 v[44:47], v67 offset:63360
	s_waitcnt vmcnt(7) lgkmcnt(1)
	v_pk_fma_f32 v[32:33], v[40:41], v[48:49], v[32:33]
	v_pk_fma_f32 v[34:35], v[42:43], v[50:51], v[34:35]
	global_store_dwordx4 v[54:55], v[32:35], off offset:512
	v_lshl_add_u64 v[54:55], v[54:55], 0, s[98:99]
	s_waitcnt vmcnt(7) lgkmcnt(0)
	v_pk_fma_f32 v[36:37], v[44:45], v[48:49], v[36:37]
	v_pk_fma_f32 v[38:39], v[46:47], v[50:51], v[38:39]
	global_store_dwordx4 v[54:55], v[36:39], off offset:512
	v_lshl_add_u64 v[54:55], v[54:55], 0, s[98:99]
	v_add_u32_e32 v67, 0x10800, v67
	s_mov_b32 s0, 0x80000
	s_mov_b32 s1, 0
	s_add_i32 s24, s24, s22
	s_cmpk_lt_i32 s24, 0x100
	s_barrier
	s_cbranch_scc1 .LBB0_1857

.LBB0_2090:
	global_load_dwordx4 v[116:119], v[70:71], off
	v_lshl_add_u64 v[120:121], v[72:73], 0, s[10:11]
	v_lshl_add_u64 v[122:123], v[72:73], 0, s[10:11]
	s_mov_b32 s98, 0x8000
	s_mov_b32 s99, 0
	global_load_dwordx4 v[76:79], v[120:121], off
	v_lshl_add_u64 v[120:121], v[120:121], 0, s[98:99]
	global_load_dwordx4 v[80:83], v[120:121], off
	v_lshl_add_u64 v[120:121], v[120:121], 0, s[98:99]
	global_load_dwordx4 v[84:87], v[120:121], off
	v_lshl_add_u64 v[120:121], v[120:121], 0, s[98:99]
	global_load_dwordx4 v[88:91], v[120:121], off
	v_lshl_add_u64 v[120:121], v[120:121], 0, s[98:99]
	global_load_dwordx4 v[92:95], v[120:121], off
	v_lshl_add_u64 v[120:121], v[120:121], 0, s[98:99]
	global_load_dwordx4 v[96:99], v[120:121], off
	v_lshl_add_u64 v[120:121], v[120:121], 0, s[98:99]
	global_load_dwordx4 v[100:103], v[120:121], off
	v_lshl_add_u64 v[120:121], v[120:121], 0, s[98:99]
	global_load_dwordx4 v[104:107], v[120:121], off
	v_lshl_add_u64 v[120:121], v[120:121], 0, s[98:99]
	ds_read_b128 v[108:111], v65 offset:0
	ds_read_b128 v[112:115], v65 offset:4224
	s_waitcnt vmcnt(7) lgkmcnt(1)
	v_pk_fma_f32 v[76:77], v[108:109], v[116:117], v[76:77]
	v_pk_fma_f32 v[78:79], v[110:111], v[118:119], v[78:79]
	global_store_dwordx4 v[122:123], v[76:79], off
	v_lshl_add_u64 v[122:123], v[122:123], 0, s[98:99]
	ds_read_b128 v[108:111], v65 offset:8448
	s_waitcnt vmcnt(7) lgkmcnt(1)
	v_pk_fma_f32 v[80:81], v[112:113], v[116:117], v[80:81]
	v_pk_fma_f32 v[82:83], v[114:115], v[118:119], v[82:83]
	global_store_dwordx4 v[122:123], v[80:83], off
	v_lshl_add_u64 v[122:123], v[122:123], 0, s[98:99]
	ds_read_b128 v[112:115], v65 offset:12672
	s_waitcnt vmcnt(7) lgkmcnt(1)
	v_pk_fma_f32 v[84:85], v[108:109], v[116:117], v[84:85]
	v_pk_fma_f32 v[86:87], v[110:111], v[118:119], v[86:87]
	global_store_dwordx4 v[122:123], v[84:87], off
	v_lshl_add_u64 v[122:123], v[122:123], 0, s[98:99]
	ds_read_b128 v[108:111], v65 offset:16896
	s_waitcnt vmcnt(7) lgkmcnt(1)
	v_pk_fma_f32 v[88:89], v[112:113], v[116:117], v[88:89]
	v_pk_fma_f32 v[90:91], v[114:115], v[118:119], v[90:91]
	global_store_dwordx4 v[122:123], v[88:91], off
	v_lshl_add_u64 v[122:123], v[122:123], 0, s[98:99]
	ds_read_b128 v[112:115], v65 offset:21120
	s_waitcnt vmcnt(7) lgkmcnt(1)
	v_pk_fma_f32 v[92:93], v[108:109], v[116:117], v[92:93]
	v_pk_fma_f32 v[94:95], v[110:111], v[118:119], v[94:95]
	global_store_dwordx4 v[122:123], v[92:95], off
	v_lshl_add_u64 v[122:123], v[122:123], 0, s[98:99]
	ds_read_b128 v[108:111], v65 offset:25344
	s_waitcnt vmcnt(7) lgkmcnt(1)
	v_pk_fma_f32 v[96:97], v[112:113], v[116:117], v[96:97]
	v_pk_fma_f32 v[98:99], v[114:115], v[118:119], v[98:99]
	global_store_dwordx4 v[122:123], v[96:99], off
	v_lshl_add_u64 v[122:123], v[122:123], 0, s[98:99]
	ds_read_b128 v[112:115], v65 offset:29568
	s_waitcnt vmcnt(7) lgkmcnt(1)
	v_pk_fma_f32 v[100:101], v[108:109], v[116:117], v[100:101]
	v_pk_fma_f32 v[102:103], v[110:111], v[118:119], v[102:103]
	global_store_dwordx4 v[122:123], v[100:103], off
	v_lshl_add_u64 v[122:123], v[122:123], 0, s[98:99]
	s_waitcnt vmcnt(7) lgkmcnt(0)
	v_pk_fma_f32 v[104:105], v[112:113], v[116:117], v[104:105]
	v_pk_fma_f32 v[106:107], v[114:115], v[118:119], v[106:107]
	global_store_dwordx4 v[122:123], v[104:107], off
	v_lshl_add_u64 v[122:123], v[122:123], 0, s[98:99]
	global_load_dwordx4 v[76:79], v[120:121], off
	v_lshl_add_u64 v[120:121], v[120:121], 0, s[98:99]
	global_load_dwordx4 v[80:83], v[120:121], off
	v_lshl_add_u64 v[120:121], v[120:121], 0, s[98:99]
	global_load_dwordx4 v[84:87], v[120:121], off
	v_lshl_add_u64 v[120:121], v[120:121], 0, s[98:99]
	global_load_dwordx4 v[88:91], v[120:121], off
	v_lshl_add_u64 v[120:121], v[120:121], 0, s[98:99]
	global_load_dwordx4 v[92:95], v[120:121], off
	v_lshl_add_u64 v[120:121], v[120:121], 0, s[98:99]
	global_load_dwordx4 v[96:99], v[120:121], off
	v_lshl_add_u64 v[120:121], v[120:121], 0, s[98:99]
	global_load_dwordx4 v[100:103], v[120:121], off
	v_lshl_add_u64 v[120:121], v[120:121], 0, s[98:99]
	global_load_dwordx4 v[104:107], v[120:121], off
	v_lshl_add_u64 v[120:121], v[120:121], 0, s[98:99]
	ds_read_b128 v[108:111], v65 offset:33792
	ds_read_b128 v[112:115], v65 offset:38016
	s_waitcnt vmcnt(7) lgkmcnt(1)
	v_pk_fma_f32 v[76:77], v[108:109], v[116:117], v[76:77]
	v_pk_fma_f32 v[78:79], v[110:111], v[118:119], v[78:79]
	global_store_dwordx4 v[122:123], v[76:79], off
	v_lshl_add_u64 v[122:123], v[122:123], 0, s[98:99]
	ds_read_b128 v[108:111], v65 offset:42240
	s_waitcnt vmcnt(7) lgkmcnt(1)
	v_pk_fma_f32 v[80:81], v[112:113], v[116:117], v[80:81]
	v_pk_fma_f32 v[82:83], v[114:115], v[118:119], v[82:83]
	global_store_dwordx4 v[122:123], v[80:83], off
	v_lshl_add_u64 v[122:123], v[122:123], 0, s[98:99]
	ds_read_b128 v[112:115], v65 offset:46464
	s_waitcnt vmcnt(7) lgkmcnt(1)
	v_pk_fma_f32 v[84:85], v[108:109], v[116:117], v[84:85]
	v_pk_fma_f32 v[86:87], v[110:111], v[118:119], v[86:87]
	global_store_dwordx4 v[122:123], v[84:87], off
	v_lshl_add_u64 v[122:123], v[122:123], 0, s[98:99]
	ds_read_b128 v[108:111], v65 offset:50688
	s_waitcnt vmcnt(7) lgkmcnt(1)
	v_pk_fma_f32 v[88:89], v[112:113], v[116:117], v[88:89]
	v_pk_fma_f32 v[90:91], v[114:115], v[118:119], v[90:91]
	global_store_dwordx4 v[122:123], v[88:91], off
	v_lshl_add_u64 v[122:123], v[122:123], 0, s[98:99]
	ds_read_b128 v[112:115], v65 offset:54912
	s_waitcnt vmcnt(7) lgkmcnt(1)
	v_pk_fma_f32 v[92:93], v[108:109], v[116:117], v[92:93]
	v_pk_fma_f32 v[94:95], v[110:111], v[118:119], v[94:95]
	global_store_dwordx4 v[122:123], v[92:95], off
	v_lshl_add_u64 v[122:123], v[122:123], 0, s[98:99]
	ds_read_b128 v[108:111], v65 offset:59136
	s_waitcnt vmcnt(7) lgkmcnt(1)
	v_pk_fma_f32 v[96:97], v[112:113], v[116:117], v[96:97]
	v_pk_fma_f32 v[98:99], v[114:115], v[118:119], v[98:99]
	global_store_dwordx4 v[122:123], v[96:99], off
	v_lshl_add_u64 v[122:123], v[122:123], 0, s[98:99]
	ds_read_b128 v[112:115], v65 offset:63360
	s_waitcnt vmcnt(7) lgkmcnt(1)
	v_pk_fma_f32 v[100:101], v[108:109], v[116:117], v[100:101]
	v_pk_fma_f32 v[102:103], v[110:111], v[118:119], v[102:103]
	global_store_dwordx4 v[122:123], v[100:103], off
	v_lshl_add_u64 v[122:123], v[122:123], 0, s[98:99]
	s_waitcnt vmcnt(7) lgkmcnt(0)
	v_pk_fma_f32 v[104:105], v[112:113], v[116:117], v[104:105]
	v_pk_fma_f32 v[106:107], v[114:115], v[118:119], v[106:107]
	global_store_dwordx4 v[122:123], v[104:107], off
	v_lshl_add_u64 v[122:123], v[122:123], 0, s[98:99]
	v_add_u32_e32 v65, 0x10800, v65
	s_mov_b32 s10, 0x80000
	s_mov_b32 s11, 0
	s_barrier
	ds_write_b128 v137, v[60:63]
	ds_write_b128 v137, v[48:51] offset:64
	ds_write_b128 v137, v[44:47] offset:8448
	ds_write_b128 v137, v[40:43] offset:8512
	ds_write_b128 v137, v[36:39] offset:16896
	ds_write_b128 v137, v[32:35] offset:16960
	ds_write_b128 v137, v[28:31] offset:25344
	ds_write_b128 v137, v[24:27] offset:25408
	ds_write_b128 v137, v[20:23] offset:33792
	ds_write_b128 v137, v[16:19] offset:33856
	ds_write_b128 v137, v[12:15] offset:42240
	ds_write_b128 v137, v[8:11] offset:42304
	ds_write_b128 v137, v[4:7] offset:50688
	ds_write_b128 v137, v[0:3] offset:50752
	ds_write_b128 v137, v[52:55] offset:59136
	ds_write_b128 v137, v[56:59] offset:59200
	s_waitcnt lgkmcnt(0)
	s_barrier
	s_and_saveexec_b64 s[10:11], s[0:1]
	s_xor_b64 s[0:1], exec, s[10:11]
	v_add_u32_e32 v132, 0xffffc000, v64
	v_lshlrev_b64 v[0:1], 12, v[132:133]
	v_lshl_add_u64 v[2:3], s[70:71], 0, v[0:1]
	s_or_saveexec_b64 s[0:1], s[0:1]
	v_mov_b64_e32 v[0:1], 0xc000
	s_xor_b64 exec, exec, s[0:1]
	v_ashrrev_i32_e32 v65, 31, v64
	v_lshlrev_b64 v[0:1], 12, v[64:65]
	v_lshl_add_u64 v[2:3], s[84:85], 0, v[0:1]
	v_ashrrev_i32_e32 v0, 11, v64
	v_mul_hi_i32_i24_e32 v1, 0x1800, v0
	v_mul_i32_i24_e32 v0, 0x1800, v0
	s_or_b64 exec, exec, s[0:1]
	v_lshl_add_u64 v[0:1], v[0:1], 2, s[4:5]
	v_lshl_add_u64 v[0:1], s[8:9], 2, v[0:1]
	v_lshlrev_b32_e32 v132, 2, v66
	v_lshl_add_u64 v[0:1], v[0:1], 0, v[132:133]
	v_lshl_add_u64 v[2:3], v[2:3], 0, v[68:69]
	s_mov_b64 s[0:1], 0
.LBB0_2096:
	global_load_dwordx4 v[48:51], v[0:1], off offset:512
	v_lshl_add_u64 v[52:53], v[2:3], 0, s[0:1]
	v_lshl_add_u64 v[54:55], v[2:3], 0, s[0:1]
	s_mov_b32 s98, 0x8000
	s_mov_b32 s99, 0
	global_load_dwordx4 v[8:11], v[52:53], off offset:512
	v_lshl_add_u64 v[52:53], v[52:53], 0, s[98:99]
	global_load_dwordx4 v[12:15], v[52:53], off offset:512
	v_lshl_add_u64 v[52:53], v[52:53], 0, s[98:99]
	global_load_dwordx4 v[16:19], v[52:53], off offset:512
	v_lshl_add_u64 v[52:53], v[52:53], 0, s[98:99]
	global_load_dwordx4 v[20:23], v[52:53], off offset:512
	v_lshl_add_u64 v[52:53], v[52:53], 0, s[98:99]
	global_load_dwordx4 v[24:27], v[52:53], off offset:512
	v_lshl_add_u64 v[52:53], v[52:53], 0, s[98:99]
	global_load_dwordx4 v[28:31], v[52:53], off offset:512
	v_lshl_add_u64 v[52:53], v[52:53], 0, s[98:99]
	global_load_dwordx4 v[32:35], v[52:53], off offset:512
	v_lshl_add_u64 v[52:53], v[52:53], 0, s[98:99]
	global_load_dwordx4 v[36:39], v[52:53], off offset:512
	v_lshl_add_u64 v[52:53], v[52:53], 0, s[98:99]
	ds_read_b128 v[40:43], v67 offset:0
	ds_read_b128 v[44:47], v67 offset:4224
	s_waitcnt vmcnt(7) lgkmcnt(1)
	v_pk_fma_f32 v[8:9], v[40:41], v[48:49], v[8:9]
	v_pk_fma_f32 v[10:11], v[42:43], v[50:51], v[10:11]
	global_store_dwordx4 v[54:55], v[8:11], off offset:512
	v_lshl_add_u64 v[54:55], v[54:55], 0, s[98:99]
	ds_read_b128 v[40:43], v67 offset:8448
	s_waitcnt vmcnt(7) lgkmcnt(1)
	v_pk_fma_f32 v[12:13], v[44:45], v[48:49], v[12:13]
	v_pk_fma_f32 v[14:15], v[46:47], v[50:51], v[14:15]
	global_store_dwordx4 v[54:55], v[12:15], off offset:512
	v_lshl_add_u64 v[54:55], v[54:55], 0, s[98:99]
	ds_read_b128 v[44:47], v67 offset:12672
	s_waitcnt vmcnt(7) lgkmcnt(1)
	v_pk_fma_f32 v[16:17], v[40:41], v[48:49], v[16:17]
	v_pk_fma_f32 v[18:19], v[42:43], v[50:51], v[18:19]
	global_store_dwordx4 v[54:55], v[16:19], off offset:512
	v_lshl_add_u64 v[54:55], v[54:55], 0, s[98:99]
	ds_read_b128 v[40:43], v67 offset:16896
	s_waitcnt vmcnt(7) lgkmcnt(1)
	v_pk_fma_f32 v[20:21], v[44:45], v[48:49], v[20:21]
	v_pk_fma_f32 v[22:23], v[46:47], v[50:51], v[22:23]
	global_store_dwordx4 v[54:55], v[20:23], off offset:512
	v_lshl_add_u64 v[54:55], v[54:55], 0, s[98:99]
	ds_read_b128 v[44:47], v67 offset:21120
	s_waitcnt vmcnt(7) lgkmcnt(1)
	v_pk_fma_f32 v[24:25], v[40:41], v[48:49], v[24:25]
	v_pk_fma_f32 v[26:27], v[42:43], v[50:51], v[26:27]
	global_store_dwordx4 v[54:55], v[24:27], off offset:512
	v_lshl_add_u64 v[54:55], v[54:55], 0, s[98:99]
	ds_read_b128 v[40:43], v67 offset:25344
	s_waitcnt vmcnt(7) lgkmcnt(1)
	v_pk_fma_f32 v[28:29], v[44:45], v[48:49], v[28:29]
	v_pk_fma_f32 v[30:31], v[46:47], v[50:51], v[30:31]
	global_store_dwordx4 v[54:55], v[28:31], off offset:512
	v_lshl_add_u64 v[54:55], v[54:55], 0, s[98:99]
	ds_read_b128 v[44:47], v67 offset:29568
	s_waitcnt vmcnt(7) lgkmcnt(1)
	v_pk_fma_f32 v[32:33], v[40:41], v[48:49], v[32:33]
	v_pk_fma_f32 v[34:35], v[42:43], v[50:51], v[34:35]
	global_store_dwordx4 v[54:55], v[32:35], off offset:512
	v_lshl_add_u64 v[54:55], v[54:55], 0, s[98:99]
	s_waitcnt vmcnt(7) lgkmcnt(0)
	v_pk_fma_f32 v[36:37], v[44:45], v[48:49], v[36:37]
	v_pk_fma_f32 v[38:39], v[46:47], v[50:51], v[38:39]
	global_store_dwordx4 v[54:55], v[36:39], off offset:512
	v_lshl_add_u64 v[54:55], v[54:55], 0, s[98:99]
	global_load_dwordx4 v[8:11], v[52:53], off offset:512
	v_lshl_add_u64 v[52:53], v[52:53], 0, s[98:99]
	global_load_dwordx4 v[12:15], v[52:53], off offset:512
	v_lshl_add_u64 v[52:53], v[52:53], 0, s[98:99]
	global_load_dwordx4 v[16:19], v[52:53], off offset:512
	v_lshl_add_u64 v[52:53], v[52:53], 0, s[98:99]
	global_load_dwordx4 v[20:23], v[52:53], off offset:512
	v_lshl_add_u64 v[52:53], v[52:53], 0, s[98:99]
	global_load_dwordx4 v[24:27], v[52:53], off offset:512
	v_lshl_add_u64 v[52:53], v[52:53], 0, s[98:99]
	global_load_dwordx4 v[28:31], v[52:53], off offset:512
	v_lshl_add_u64 v[52:53], v[52:53], 0, s[98:99]
	global_load_dwordx4 v[32:35], v[52:53], off offset:512
	v_lshl_add_u64 v[52:53], v[52:53], 0, s[98:99]
	global_load_dwordx4 v[36:39], v[52:53], off offset:512
	v_lshl_add_u64 v[52:53], v[52:53], 0, s[98:99]
	ds_read_b128 v[40:43], v67 offset:33792
	ds_read_b128 v[44:47], v67 offset:38016
	s_waitcnt vmcnt(7) lgkmcnt(1)
	v_pk_fma_f32 v[8:9], v[40:41], v[48:49], v[8:9]
	v_pk_fma_f32 v[10:11], v[42:43], v[50:51], v[10:11]
	global_store_dwordx4 v[54:55], v[8:11], off offset:512
	v_lshl_add_u64 v[54:55], v[54:55], 0, s[98:99]
	ds_read_b128 v[40:43], v67 offset:42240
	s_waitcnt vmcnt(7) lgkmcnt(1)
	v_pk_fma_f32 v[12:13], v[44:45], v[48:49], v[12:13]
	v_pk_fma_f32 v[14:15], v[46:47], v[50:51], v[14:15]
	global_store_dwordx4 v[54:55], v[12:15], off offset:512
	v_lshl_add_u64 v[54:55], v[54:55], 0, s[98:99]
	ds_read_b128 v[44:47], v67 offset:46464
	s_waitcnt vmcnt(7) lgkmcnt(1)
	v_pk_fma_f32 v[16:17], v[40:41], v[48:49], v[16:17]
	v_pk_fma_f32 v[18:19], v[42:43], v[50:51], v[18:19]
	global_store_dwordx4 v[54:55], v[16:19], off offset:512
	v_lshl_add_u64 v[54:55], v[54:55], 0, s[98:99]
	ds_read_b128 v[40:43], v67 offset:50688
	s_waitcnt vmcnt(7) lgkmcnt(1)
	v_pk_fma_f32 v[20:21], v[44:45], v[48:49], v[20:21]
	v_pk_fma_f32 v[22:23], v[46:47], v[50:51], v[22:23]
	global_store_dwordx4 v[54:55], v[20:23], off offset:512
	v_lshl_add_u64 v[54:55], v[54:55], 0, s[98:99]
	ds_read_b128 v[44:47], v67 offset:54912
	s_waitcnt vmcnt(7) lgkmcnt(1)
	v_pk_fma_f32 v[24:25], v[40:41], v[48:49], v[24:25]
	v_pk_fma_f32 v[26:27], v[42:43], v[50:51], v[26:27]
	global_store_dwordx4 v[54:55], v[24:27], off offset:512
	v_lshl_add_u64 v[54:55], v[54:55], 0, s[98:99]
	ds_read_b128 v[40:43], v67 offset:59136
	s_waitcnt vmcnt(7) lgkmcnt(1)
	v_pk_fma_f32 v[28:29], v[44:45], v[48:49], v[28:29]
	v_pk_fma_f32 v[30:31], v[46:47], v[50:51], v[30:31]
	global_store_dwordx4 v[54:55], v[28:31], off offset:512
	v_lshl_add_u64 v[54:55], v[54:55], 0, s[98:99]
	ds_read_b128 v[44:47], v67 offset:63360
	s_waitcnt vmcnt(7) lgkmcnt(1)
	v_pk_fma_f32 v[32:33], v[40:41], v[48:49], v[32:33]
	v_pk_fma_f32 v[34:35], v[42:43], v[50:51], v[34:35]
	global_store_dwordx4 v[54:55], v[32:35], off offset:512
	v_lshl_add_u64 v[54:55], v[54:55], 0, s[98:99]
	s_waitcnt vmcnt(7) lgkmcnt(0)
	v_pk_fma_f32 v[36:37], v[44:45], v[48:49], v[36:37]
	v_pk_fma_f32 v[38:39], v[46:47], v[50:51], v[38:39]
	global_store_dwordx4 v[54:55], v[36:39], off offset:512
	v_lshl_add_u64 v[54:55], v[54:55], 0, s[98:99]
	v_add_u32_e32 v67, 0x10800, v67
	s_mov_b32 s0, 0x80000
	s_mov_b32 s1, 0
	s_add_i32 s2, s2, s22
	s_cmpk_lt_i32 s2, 0x100
	s_barrier
	s_cbranch_scc1 .LBB0_2081
